# gdn chain: KT scaling + the two masked decayed attention tiles per wave rewritten branch-free with all LDS operand reads up front (counted lgkmcnt)
# baseline (speedup 1.0000x reference)
; #define LAS __attribute__((address_space(3)))
; __device__ __forceinline__ bf16_t f2bf(float f) { return (bf16_t)(pk2(f, f) & 0xFFFFu); }
; #define MFMA16(a, b, c) __builtin_amdgcn_mfma_f32_16x16x32_bf16((a), (b), (c), 0, 0, 0)
; template <int MODE>
; __device__ NOINL void chain_item(const LAS Params* lp, int l, int item, bool ctx_out, LAS unsigned char* lds) {
;     ...
;         if (MODE == 0) {
;             const float sc = __expf(gcs[63] - gcs[pp]);
;             {
;                 float kf[16]; unpack8(kk0, kf); unpack8(kk1, kf + 8);
; #pragma unroll
;                 for (int e = 0; e < 16; ++e) KT[(lrow + e) * 72 + ppz] = f2bf(kf[e] * sc);
;             }
;             const int ct = w >> 1;
; #pragma unroll
;             for (int jj = 0; jj < 2; ++jj) {
;                 const int st = 2 * (w & 1) + jj; f32x4 acc = {0.f, 0.f, 0.f, 0.f};
; #pragma unroll
;                 for (int ks = 0; ks < 4; ++ks) {
;                     const bf16x8 A = *(const LAS bf16x8*)(Qs + (16 * ct + fr) * 136 + ks * 32 + fq * 8), B = *(const LAS bf16x8*)(Ks + (16 * st + fr) * 136 + ks * 32 + fq * 8);
;                     acc = MFMA16(A, B, acc);
;                 }
;                 const int s = 16 * st + fr; const float gs = gcs[s];
; #pragma unroll
;                 for (int j = 0; j < 4; ++j) { const int c = 16 * ct + 4 * fq + j; AT[c * 72 + s] = f2bf(s <= c ? acc[j] * __expf(gcs[c] - gs) : 0.f); }
;             }
.LBB0_1149:
	v_mov_b32_e32 v76, s16
	ds_read_b32 v76, v76
	ds_read_b32 v77, v153
	ds_read_b128 v[88:91], v112
	ds_read_b128 v[92:95], v112 offset:64
	ds_read_b128 v[96:99], v112 offset:128
	ds_read_b128 v[100:103], v112 offset:192
	ds_read_b128 v[104:107], v192 offset:17408
	ds_read_b128 v[194:197], v192 offset:17472
	ds_read_b128 v[198:201], v192 offset:17536
	ds_read_b128 v[232:235], v192 offset:17600
	ds_read_b32 v85, v164
	ds_read_b32 v86, v174
	ds_read_b32 v87, v166
	ds_read_b32 v148, v168
	ds_read_b32 v149, v170
	ds_read_b32 v193, v172
	v_lshlrev_b32_e32 v78, 16, v73
	v_lshlrev_b32_e32 v81, 16, v68
	v_and_b32_e32 v68, 0xffff0000, v68
	v_and_b32_e32 v73, 0xffff0000, v73
	s_waitcnt lgkmcnt(14)
	v_sub_f32_e32 v76, v76, v77
	v_mul_f32_e32 v76, 0x3fb8aa3b, v76
	v_exp_f32_e32 v76, v76
	v_lshlrev_b32_e32 v77, 16, v72
	v_and_b32_e32 v72, 0xffff0000, v72
	v_lshlrev_b32_e32 v82, 16, v69
	v_mul_f32_e32 v72, v76, v72
	v_cvt_pk_bf16_f32 v72, v72, s0
	ds_write_b16 v185, v72 offset:34960
	v_mul_f32_e32 v72, v76, v78
	v_mul_f32_e32 v68, v76, v68
	v_cvt_pk_bf16_f32 v72, v72, s0
	v_cvt_pk_bf16_f32 v68, v68, s0
	ds_write_b16 v185, v72 offset:35104
	v_mul_f32_e32 v72, v76, v73
	ds_write_b16 v185, v68 offset:36112
	v_mul_f32_e32 v68, v76, v82
	v_lshlrev_b32_e32 v79, 16, v74
	v_and_b32_e32 v69, 0xffff0000, v69
	v_cvt_pk_bf16_f32 v72, v72, s0
	v_cvt_pk_bf16_f32 v68, v68, s0
	ds_write_b16 v185, v72 offset:35248
	v_mul_f32_e32 v72, v76, v79
	ds_write_b16 v185, v68 offset:36256
	v_mul_f32_e32 v68, v76, v69
	v_and_b32_e32 v74, 0xffff0000, v74
	v_lshlrev_b32_e32 v83, 16, v70
	v_cvt_pk_bf16_f32 v72, v72, s0
	v_cvt_pk_bf16_f32 v68, v68, s0
	ds_write_b16 v185, v72 offset:35392
	v_mul_f32_e32 v72, v76, v74
	ds_write_b16 v185, v68 offset:36400
	v_mul_f32_e32 v68, v76, v83
	v_lshlrev_b32_e32 v80, 16, v75
	v_and_b32_e32 v70, 0xffff0000, v70
	v_cvt_pk_bf16_f32 v72, v72, s0
	v_cvt_pk_bf16_f32 v68, v68, s0
	ds_write_b16 v185, v72 offset:35536
	v_mul_f32_e32 v72, v76, v80
	ds_write_b16 v185, v68 offset:36544
	v_mul_f32_e32 v68, v76, v70
	v_and_b32_e32 v75, 0xffff0000, v75
	v_lshlrev_b32_e32 v84, 16, v71
	v_cvt_pk_bf16_f32 v72, v72, s0
	v_cvt_pk_bf16_f32 v68, v68, s0
	ds_write_b16 v185, v72 offset:35680
	v_mul_f32_e32 v72, v76, v75
	ds_write_b16 v185, v68 offset:36688
	v_mul_f32_e32 v68, v76, v84
	v_and_b32_e32 v71, 0xffff0000, v71
	v_cvt_pk_bf16_f32 v72, v72, s0
	v_cvt_pk_bf16_f32 v68, v68, s0
	v_mul_f32_e32 v77, v76, v77
	ds_write_b16 v185, v72 offset:35824
	v_mul_f32_e32 v72, v76, v81
	ds_write_b16 v185, v68 offset:36832
	v_mul_f32_e32 v68, v76, v71
	v_cvt_pk_bf16_f32 v77, v77, s0
	v_cvt_pk_bf16_f32 v72, v72, s0
	v_cvt_pk_bf16_f32 v68, v68, s0
	ds_write_b16 v185, v77 offset:34816
	ds_write_b16 v185, v72 offset:35968
	ds_write_b16 v185, v68 offset:36976
	ds_read_b128 v[236:239], v192 offset:21760
	ds_read_b128 v[240:243], v192 offset:21824
	ds_read_b128 v[244:247], v192 offset:21888
	ds_read_b128 v[248:251], v192 offset:21952
	s_waitcnt lgkmcnt(14)
	v_mfma_f32_16x16x32_bf16 v[68:71], v[88:91], v[104:107], 0
	v_mfma_f32_16x16x32_bf16 v[68:71], v[92:95], v[194:197], v[68:71]
	v_mfma_f32_16x16x32_bf16 v[68:71], v[96:99], v[198:201], v[68:71]
	v_mfma_f32_16x16x32_bf16 v[68:71], v[100:103], v[232:235], v[68:71]
	s_waitcnt lgkmcnt(3)
	v_mfma_f32_16x16x32_bf16 v[72:75], v[88:91], v[236:239], 0
	s_waitcnt lgkmcnt(2)
	v_mfma_f32_16x16x32_bf16 v[72:75], v[92:95], v[240:243], v[72:75]
	s_waitcnt lgkmcnt(1)
	v_mfma_f32_16x16x32_bf16 v[72:75], v[96:99], v[244:247], v[72:75]
	s_waitcnt lgkmcnt(0)
	v_mfma_f32_16x16x32_bf16 v[72:75], v[100:103], v[248:251], v[72:75]
	v_sub_f32_e32 v76, v87, v85
	v_sub_f32_e32 v77, v148, v85
	v_sub_f32_e32 v78, v149, v85
	v_sub_f32_e32 v79, v193, v85
	v_sub_f32_e32 v80, v87, v86
	v_sub_f32_e32 v81, v148, v86
	v_sub_f32_e32 v82, v149, v86
	v_sub_f32_e32 v83, v193, v86
	v_mul_f32_e32 v76, 0x3fb8aa3b, v76
	v_mul_f32_e32 v77, 0x3fb8aa3b, v77
	v_mul_f32_e32 v78, 0x3fb8aa3b, v78
	v_mul_f32_e32 v79, 0x3fb8aa3b, v79
	v_mul_f32_e32 v80, 0x3fb8aa3b, v80
	v_mul_f32_e32 v81, 0x3fb8aa3b, v81
	v_mul_f32_e32 v82, 0x3fb8aa3b, v82
	v_mul_f32_e32 v83, 0x3fb8aa3b, v83
	v_exp_f32_e32 v76, v76
	v_exp_f32_e32 v77, v77
	v_exp_f32_e32 v78, v78
	v_exp_f32_e32 v79, v79
	v_exp_f32_e32 v80, v80
	v_exp_f32_e32 v81, v81
	v_exp_f32_e32 v82, v82
	v_exp_f32_e32 v83, v83
	v_add_u32_e32 v88, v165, v167
	v_add_u32_e32 v89, v165, v169
	v_add_u32_e32 v90, v165, v171
	v_add_u32_e32 v91, v165, v173
	v_mul_f32_e32 v76, v68, v76
	v_mul_f32_e32 v77, v69, v77
	v_mul_f32_e32 v78, v70, v78
	v_mul_f32_e32 v79, v71, v79
	v_mul_f32_e32 v80, v72, v80
	v_mul_f32_e32 v81, v73, v81
	v_mul_f32_e32 v82, v74, v82
	v_mul_f32_e32 v83, v75, v83
	v_cvt_pk_bf16_f32 v76, v76, v76
	v_cvt_pk_bf16_f32 v77, v77, v77
	v_cvt_pk_bf16_f32 v78, v78, v78
	v_cvt_pk_bf16_f32 v79, v79, v79
	v_cvt_pk_bf16_f32 v80, v80, v80
	v_cvt_pk_bf16_f32 v81, v81, v81
	v_cvt_pk_bf16_f32 v82, v82, v82
	v_cvt_pk_bf16_f32 v83, v83, v83
	v_cndmask_b32_e64 v76, 0, v76, s[46:47]
	v_cndmask_b32_e64 v77, 0, v77, s[48:49]
	v_cndmask_b32_e64 v78, 0, v78, s[50:51]
	v_cndmask_b32_e64 v79, 0, v79, s[52:53]
	v_cndmask_b32_e64 v80, 0, v80, s[54:55]
	v_cndmask_b32_e64 v81, 0, v81, s[56:57]
	v_cndmask_b32_e64 v82, 0, v82, s[58:59]
	v_cndmask_b32_e64 v68, 0, v83, s[60:61]
	ds_write_b16 v88, v76
	ds_write_b16 v89, v77
	ds_write_b16 v90, v78
	ds_write_b16 v91, v79
	ds_write_b16 v175, v80
	ds_write_b16 v176, v81
	ds_write_b16 v177, v82
	s_branch .LBB0_1141
